# pair8l with the P6 per-row s_barrier moved from the loop top to just after the row loads are issued
# speedup vs baseline: 1.0082x; 1.0082x over previous
; __device__ __forceinline__ void p6_final_ln(const Frame& F) {
;     ...
;     for (int m = gw; m < M; m += NGW) {
;         const float* xr = (m < SEQ) ? F.xp + (size_t)m * DM : F.xs + (size_t)(m - SEQ) * DM;
;         const bf16_t* orow = F.OUTB + (size_t)m * DM;
;         f32x4 z[16]; float s = 0.f;
; #pragma unroll
;         for (int j = 0; j < 8; ++j) { const int col = j * 512 + lane * 8;
;             const f32x4 xa = *(const f32x4*)(xr + col), xb = *(const f32x4*)(xr + col + 4); const u32x4 o = *(const u32x4*)(orow + col);
;             z[2 * j]     = xa * DN_ALPHA + (f32x4){bflo(o.x), bfhi(o.x), bflo(o.y), bfhi(o.y)};
;             z[2 * j + 1] = xb * DN_ALPHA + (f32x4){bflo(o.z), bfhi(o.z), bflo(o.w), bfhi(o.w)};
;             s += (z[2 * j][0] + z[2 * j][1]) + (z[2 * j][2] + z[2 * j][3]) + (z[2 * j + 1][0] + z[2 * j + 1][1]) + (z[2 * j + 1][2] + z[2 * j + 1][3]); }
.LBB0_575:
	s_lshl_b64 s[18:19], s[12:13], 13
	s_add_u32 s18, s26, s18
	s_addc_u32 s19, s27, s19
	v_lshlrev_b32_e32 v70, 1, v4
	global_load_dwordx4 v[42:45], v70, s[18:19]
	global_load_dwordx4 v[46:49], v70, s[18:19] offset:1024
	global_load_dwordx4 v[50:53], v70, s[18:19] offset:2048
	v_lshlrev_b32_e32 v109, 2, v4
	global_load_dwordx4 v[54:57], v109, s[16:17]
	global_load_dwordx4 v[58:61], v109, s[16:17] offset:16
	global_load_dwordx4 v[62:65], v109, s[16:17] offset:2048
	global_load_dwordx4 v[66:69], v109, s[16:17] offset:2064
	global_load_dwordx4 v[74:77], v104, s[16:17]
	global_load_dwordx4 v[78:81], v104, s[16:17] offset:16
	global_load_dwordx4 v[0:3], v105, s[16:17] offset:16
	global_load_dwordx4 v[82:85], v105, s[16:17]
	v_lshlrev_b32_e32 v107, 2, v6
	v_lshlrev_b32_e32 v71, 1, v6
	v_lshlrev_b32_e32 v108, 2, v8
	v_lshlrev_b32_e32 v72, 1, v8
	global_load_dwordx4 v[86:89], v107, s[16:17] offset:16
	global_load_dwordx4 v[94:97], v107, s[16:17]
	global_load_dwordx4 v[112:115], v108, s[16:17] offset:16
	global_load_dwordx4 v[116:119], v108, s[16:17]
	global_load_dwordx4 v[98:101], v70, s[18:19] offset:3072
	global_load_dwordx4 v[120:123], v71, s[18:19]
	global_load_dwordx4 v[124:127], v72, s[18:19]
	s_lshl_b64 s[12:13], s[12:13], 14
	s_add_u32 s12, s38, s12
	s_addc_u32 s13, s39, s13
	s_add_u32 s0, s0, s2
	s_addc_u32 s1, s1, s3
	s_add_u32 s6, s6, s8
	s_addc_u32 s7, s7, s9
	s_cmpk_lt_i32 s0, 0x6000
	s_barrier
	s_waitcnt vmcnt(17)
	v_lshlrev_b32_e32 v70, 16, v42
	v_and_b32_e32 v71, 0xffff0000, v42
	v_lshlrev_b32_e32 v42, 16, v43
	v_and_b32_e32 v43, 0xffff0000, v43
	v_lshlrev_b32_e32 v72, 16, v44
	v_and_b32_e32 v73, 0xffff0000, v44
	v_lshlrev_b32_e32 v44, 16, v45
	v_and_b32_e32 v45, 0xffff0000, v45
	s_waitcnt vmcnt(16)
	v_lshlrev_b32_e32 v110, 16, v46
	v_and_b32_e32 v111, 0xffff0000, v46
	v_lshlrev_b32_e32 v46, 16, v47
	v_and_b32_e32 v47, 0xffff0000, v47
	v_lshlrev_b32_e32 v128, 16, v48
	v_and_b32_e32 v129, 0xffff0000, v48
	v_lshlrev_b32_e32 v48, 16, v49
	v_and_b32_e32 v49, 0xffff0000, v49
	s_waitcnt vmcnt(14)
	v_pk_fma_f32 v[90:91], v[56:57], s[10:11], v[42:43] op_sel_hi:[1,0,1]
	v_pk_fma_f32 v[92:93], v[54:55], s[10:11], v[70:71] op_sel_hi:[1,0,1]
	s_waitcnt vmcnt(13)
	v_pk_fma_f32 v[70:71], v[60:61], s[10:11], v[44:45] op_sel_hi:[1,0,1]
	v_pk_fma_f32 v[72:73], v[58:59], s[10:11], v[72:73] op_sel_hi:[1,0,1]
	s_waitcnt vmcnt(12)
	v_pk_fma_f32 v[60:61], v[64:65], s[10:11], v[46:47] op_sel_hi:[1,0,1]
	v_pk_fma_f32 v[58:59], v[62:63], s[10:11], v[110:111] op_sel_hi:[1,0,1]
	s_waitcnt vmcnt(11)
	v_pk_fma_f32 v[56:57], v[68:69], s[10:11], v[48:49] op_sel_hi:[1,0,1]
	v_pk_fma_f32 v[54:55], v[66:67], s[10:11], v[128:129] op_sel_hi:[1,0,1]
	v_mov_b32_e32 v46, v92
	v_mov_b32_e32 v47, v58
	v_mov_b32_e32 v48, v93
	v_mov_b32_e32 v49, v59
	v_mov_b32_e32 v62, v90
	v_mov_b32_e32 v63, v60
	v_mov_b32_e32 v64, v91
	v_mov_b32_e32 v65, v61
	v_lshlrev_b32_e32 v130, 16, v50
	v_and_b32_e32 v131, 0xffff0000, v50
	v_lshlrev_b32_e32 v50, 16, v51
	v_and_b32_e32 v51, 0xffff0000, v51
	v_mov_b32_e32 v66, v72
	v_mov_b32_e32 v67, v54
	v_mov_b32_e32 v68, v73
	v_mov_b32_e32 v69, v55
	v_pk_add_f32 v[46:47], v[46:47], v[48:49]
	v_pk_add_f32 v[48:49], v[62:63], v[64:65]
	v_lshlrev_b32_e32 v132, 16, v52
	v_and_b32_e32 v133, 0xffff0000, v52
	v_lshlrev_b32_e32 v134, 16, v53
	v_and_b32_e32 v135, 0xffff0000, v53
	s_waitcnt vmcnt(10)
	v_pk_fma_f32 v[52:53], v[76:77], s[10:11], v[50:51] op_sel_hi:[1,0,1]
	v_pk_fma_f32 v[50:51], v[74:75], s[10:11], v[130:131] op_sel_hi:[1,0,1]
	v_mov_b32_e32 v74, v70
	v_mov_b32_e32 v75, v56
	v_mov_b32_e32 v76, v71
	v_mov_b32_e32 v77, v57
	v_pk_add_f32 v[62:63], v[66:67], v[68:69]
	v_pk_add_f32 v[46:47], v[46:47], v[48:49]
	v_pk_add_f32 v[64:65], v[74:75], v[76:77]
	v_pk_add_f32 v[46:47], v[62:63], v[46:47]
	s_waitcnt vmcnt(9)
	v_pk_fma_f32 v[44:45], v[80:81], s[10:11], v[134:135] op_sel_hi:[1,0,1]
	v_pk_fma_f32 v[42:43], v[78:79], s[10:11], v[132:133] op_sel_hi:[1,0,1]
	v_pk_mov_b32 v[78:79], v[50:51], v[52:53] op_sel:[1,0]
	v_mov_b32_e32 v80, v50
	v_mov_b32_e32 v81, v53
	v_pk_add_f32 v[46:47], v[64:65], v[46:47]
	v_pk_add_f32 v[66:67], v[78:79], v[80:81]
	v_add_f32_e32 v46, 0, v46
	v_mov_b32_e32 v48, v44
	v_mov_b32_e32 v49, v42
	v_mov_b32_e32 v62, v45
	v_mov_b32_e32 v63, v43
	v_add_f32_e32 v76, v46, v47
	v_pk_add_f32 v[46:47], v[66:67], v[66:67] op_sel:[0,1] op_sel_hi:[1,0]
	v_pk_add_f32 v[62:63], v[48:49], v[62:63]
	v_lshlrev_b32_e32 v111, 2, v10
	v_pk_add_f32 v[64:65], v[62:63], v[46:47] op_sel:[1,0] op_sel_hi:[0,1]
	v_lshlrev_b32_e32 v46, 1, v10
	global_load_dwordx4 v[46:49], v46, s[18:19]
	v_pk_add_f32 v[78:79], v[62:63], v[64:65]
	global_load_dwordx4 v[62:65], v111, s[16:17] offset:16
	global_load_dwordx4 v[66:69], v111, s[16:17]
	v_lshlrev_b32_e32 v77, 1, v12
	global_load_dwordx4 v[128:131], v77, s[18:19]
	v_lshlrev_b32_e32 v110, 2, v12
	global_load_dwordx4 v[132:135], v110, s[16:17] offset:16
	global_load_dwordx4 v[136:139], v110, s[16:17]
	s_waitcnt vmcnt(8)
	v_lshlrev_b32_e32 v74, 16, v98
	v_and_b32_e32 v75, 0xffff0000, v98
	v_lshlrev_b32_e32 v80, 16, v99
	v_and_b32_e32 v81, 0xffff0000, v99
	v_pk_fma_f32 v[80:81], v[84:85], s[10:11], v[80:81] op_sel_hi:[1,0,1]
	v_pk_fma_f32 v[74:75], v[82:83], s[10:11], v[74:75] op_sel_hi:[1,0,1]
	v_lshlrev_b32_e32 v82, 16, v100
	v_and_b32_e32 v83, 0xffff0000, v100
	v_lshlrev_b32_e32 v84, 16, v101
	v_and_b32_e32 v85, 0xffff0000, v101
	v_pk_fma_f32 v[100:101], v[2:3], s[10:11], v[84:85] op_sel_hi:[1,0,1]
	v_pk_fma_f32 v[98:99], v[0:1], s[10:11], v[82:83] op_sel_hi:[1,0,1]
	s_waitcnt vmcnt(7)
; __device__ __forceinline__ float wave_sum(float v) {
; #pragma unroll
;     for (int o = 1; o < 64; o <<= 1) v += __shfl_xor(v, o);
;     return v;
; __device__ __forceinline__ void p6_final_ln(const Frame& F) {
;     ...
;         for (int j = 0; j < 8; ++j) { const int col = j * 512 + lane * 8;
;             const f32x4 xa = *(const f32x4*)(xr + col), xb = *(const f32x4*)(xr + col + 4); const u32x4 o = *(const u32x4*)(orow + col);
;             z[2 * j]     = xa * DN_ALPHA + (f32x4){bflo(o.x), bfhi(o.x), bflo(o.y), bfhi(o.y)};
;             z[2 * j + 1] = xb * DN_ALPHA + (f32x4){bflo(o.z), bfhi(o.z), bflo(o.w), bfhi(o.w)};
;             s += (z[2 * j][0] + z[2 * j][1]) + (z[2 * j][2] + z[2 * j][3]) + (z[2 * j + 1][0] + z[2 * j + 1][1]) + (z[2 * j + 1][2] + z[2 * j + 1][3]); }
;         const float mean = wave_sum(s) * (1.f / DM); float q = 0.f;
	v_lshlrev_b32_e32 v82, 16, v120
	v_and_b32_e32 v83, 0xffff0000, v120
	v_lshlrev_b32_e32 v84, 16, v121
	v_and_b32_e32 v85, 0xffff0000, v121
	v_pk_fma_f32 v[96:97], v[96:97], s[10:11], v[84:85] op_sel_hi:[1,0,1]
	v_pk_fma_f32 v[94:95], v[94:95], s[10:11], v[82:83] op_sel_hi:[1,0,1]
	v_lshlrev_b32_e32 v82, 16, v122
	v_and_b32_e32 v83, 0xffff0000, v122
	v_lshlrev_b32_e32 v84, 16, v123
	v_and_b32_e32 v85, 0xffff0000, v123
	v_add_f32_e32 v0, v74, v75
	v_add_f32_e32 v2, v80, v81
	v_pk_fma_f32 v[84:85], v[88:89], s[10:11], v[84:85] op_sel_hi:[1,0,1]
	v_pk_fma_f32 v[82:83], v[86:87], s[10:11], v[82:83] op_sel_hi:[1,0,1]
	v_mov_b32_e32 v86, v98
	v_mov_b32_e32 v87, v94
	v_mov_b32_e32 v88, v99
	v_mov_b32_e32 v89, v95
	v_mov_b32_e32 v1, v96
	v_mov_b32_e32 v3, v97
	v_pk_add_f32 v[86:87], v[86:87], v[88:89]
	v_pk_add_f32 v[0:1], v[0:1], v[2:3]
	v_mov_b32_e32 v2, v100
	v_pk_add_f32 v[0:1], v[86:87], v[0:1]
	v_mov_b32_e32 v3, v82
	v_mov_b32_e32 v86, v101
	v_mov_b32_e32 v87, v83
	v_pk_add_f32 v[2:3], v[2:3], v[86:87]
	v_mov_b32_e32 v77, v84
	v_mov_b32_e32 v79, v85
	v_pk_add_f32 v[0:1], v[2:3], v[0:1]
	v_pk_add_f32 v[2:3], v[76:77], v[78:79]
	s_nop 0
	v_pk_add_f32 v[0:1], v[2:3], v[0:1]
	s_waitcnt vmcnt(6)
	v_lshlrev_b32_e32 v2, 16, v125
	v_pk_add_f32 v[120:121], v[0:1], v[0:1] op_sel:[0,1] op_sel_hi:[1,0]
	v_lshlrev_b32_e32 v0, 16, v124
	v_and_b32_e32 v1, 0xffff0000, v124
	v_and_b32_e32 v3, 0xffff0000, v125
	v_pk_fma_f32 v[88:89], v[118:119], s[10:11], v[2:3] op_sel_hi:[1,0,1]
	v_pk_fma_f32 v[86:87], v[116:117], s[10:11], v[0:1] op_sel_hi:[1,0,1]
	v_lshlrev_b32_e32 v0, 16, v126
	v_and_b32_e32 v1, 0xffff0000, v126
	v_lshlrev_b32_e32 v2, 16, v127
	v_and_b32_e32 v3, 0xffff0000, v127
	v_pk_fma_f32 v[78:79], v[114:115], s[10:11], v[2:3] op_sel_hi:[1,0,1]
	v_pk_fma_f32 v[76:77], v[112:113], s[10:11], v[0:1] op_sel_hi:[1,0,1]
	v_pk_mov_b32 v[0:1], v[86:87], v[88:89] op_sel:[1,0]
	v_mov_b32_e32 v2, v86
	v_mov_b32_e32 v3, v89
	v_pk_add_f32 v[0:1], v[0:1], v[2:3]
	v_mov_b32_e32 v2, v78
	v_mov_b32_e32 v3, v76
	v_mov_b32_e32 v112, v79
	v_mov_b32_e32 v113, v77
	v_pk_add_f32 v[0:1], v[0:1], v[0:1] op_sel:[0,1] op_sel_hi:[1,0]
	v_pk_add_f32 v[2:3], v[2:3], v[112:113]
	s_nop 0
	v_pk_add_f32 v[0:1], v[2:3], v[0:1] op_sel:[1,0] op_sel_hi:[0,1]
	v_pk_add_f32 v[112:113], v[2:3], v[0:1]
	s_waitcnt vmcnt(5)
	v_lshlrev_b32_e32 v0, 16, v46
	v_and_b32_e32 v1, 0xffff0000, v46
	v_lshlrev_b32_e32 v2, 16, v47
	v_and_b32_e32 v3, 0xffff0000, v47
	s_waitcnt vmcnt(3)
	v_pk_fma_f32 v[68:69], v[68:69], s[10:11], v[2:3] op_sel_hi:[1,0,1]
	v_pk_fma_f32 v[66:67], v[66:67], s[10:11], v[0:1] op_sel_hi:[1,0,1]
	v_lshlrev_b32_e32 v0, 16, v48
	v_and_b32_e32 v1, 0xffff0000, v48
	v_lshlrev_b32_e32 v2, 16, v49
	v_and_b32_e32 v3, 0xffff0000, v49
	v_pk_fma_f32 v[64:65], v[64:65], s[10:11], v[2:3] op_sel_hi:[1,0,1]
	v_pk_fma_f32 v[62:63], v[62:63], s[10:11], v[0:1] op_sel_hi:[1,0,1]
	s_waitcnt vmcnt(2)
	v_lshlrev_b32_e32 v2, 16, v128
	v_and_b32_e32 v3, 0xffff0000, v128
	v_lshlrev_b32_e32 v0, 16, v129
	v_and_b32_e32 v1, 0xffff0000, v129
	s_waitcnt vmcnt(0)
	v_pk_fma_f32 v[0:1], v[138:139], s[10:11], v[0:1] op_sel_hi:[1,0,1]
	v_pk_fma_f32 v[2:3], v[136:137], s[10:11], v[2:3] op_sel_hi:[1,0,1]
	v_add_f32_e32 v114, v66, v67
	v_add_f32_e32 v116, v68, v69
	v_lshlrev_b32_e32 v48, 16, v130
	v_and_b32_e32 v49, 0xffff0000, v130
	v_mov_b32_e32 v118, v62
	v_mov_b32_e32 v119, v2
	v_mov_b32_e32 v122, v63
	v_mov_b32_e32 v123, v3
	v_mov_b32_e32 v115, v0
	v_mov_b32_e32 v117, v1
	v_lshlrev_b32_e32 v46, 16, v131
	v_and_b32_e32 v47, 0xffff0000, v131
	v_pk_fma_f32 v[48:49], v[132:133], s[10:11], v[48:49] op_sel_hi:[1,0,1]
	v_pk_add_f32 v[118:119], v[118:119], v[122:123]
	v_pk_add_f32 v[114:115], v[114:115], v[116:117]
	v_pk_fma_f32 v[46:47], v[134:135], s[10:11], v[46:47] op_sel_hi:[1,0,1]
	v_pk_add_f32 v[114:115], v[118:119], v[114:115]
	v_mov_b32_e32 v116, v64
	v_mov_b32_e32 v117, v48
	v_mov_b32_e32 v118, v65
	v_mov_b32_e32 v119, v49
	v_pk_add_f32 v[116:117], v[116:117], v[118:119]
	v_mov_b32_e32 v121, v46
	v_mov_b32_e32 v113, v47
	v_pk_add_f32 v[114:115], v[116:117], v[114:115]
	v_pk_add_f32 v[112:113], v[120:121], v[112:113]
	s_nop 0
	v_pk_add_f32 v[112:113], v[112:113], v[114:115]
	s_nop 0
	v_add_f32_e32 v102, v112, v113
	ds_bpermute_b32 v112, v5, v102
	s_waitcnt lgkmcnt(0)
	v_add_f32_e32 v102, v102, v112
	ds_bpermute_b32 v112, v7, v102
	s_waitcnt lgkmcnt(0)
	v_add_f32_e32 v102, v102, v112
	ds_bpermute_b32 v112, v9, v102
	s_waitcnt lgkmcnt(0)
	v_add_f32_e32 v102, v102, v112
	ds_bpermute_b32 v112, v11, v102
	s_waitcnt lgkmcnt(0)
	v_add_f32_e32 v102, v102, v112
	ds_bpermute_b32 v112, v13, v102
	s_waitcnt lgkmcnt(0)
	v_add_f32_e32 v102, v102, v112
	ds_bpermute_b32 v112, v103, v102
	s_waitcnt lgkmcnt(0)
; __device__ __forceinline__ void p6_final_ln(const Frame& F) {
;     ...
;         const float mean = wave_sum(s) * (1.f / DM); float q = 0.f;
; #pragma unroll
;         for (int j = 0; j < 16; ++j) { const f32x4 d = z[j] - mean; z[j] = d; q += (d[0] * d[0] + d[1] * d[1]) + (d[2] * d[2] + d[3] * d[3]); }
;         const float rstd = __builtin_amdgcn_rsqf(wave_sum(q) * (1.f / DM) + LN_EPS);
;         float* yr = F.out + (size_t)m * DM;
; #pragma unroll
;         for (int j = 0; j < 8; ++j) { const int col = j * 512 + lane * 8;
;             const f32x4 ga = *(const f32x4*)(F.ln_g + col), gb = *(const f32x4*)(F.ln_g + col + 4), ba = *(const f32x4*)(F.ln_b + col), bb = *(const f32x4*)(F.ln_b + col + 4);
	v_add_f32_e32 v136, v102, v112
	v_fmamk_f32 v93, v136, 0xb9800000, v93
	v_fmac_f32_e32 v92, 0xb9800000, v136
	v_fmamk_f32 v91, v136, 0xb9800000, v91
	v_fmac_f32_e32 v90, 0xb9800000, v136
	v_pk_mul_f32 v[112:113], v[90:91], v[90:91]
	v_pk_mul_f32 v[114:115], v[92:93], v[92:93]
	v_fmamk_f32 v73, v136, 0xb9800000, v73
	v_pk_mov_b32 v[116:117], v[114:115], v[112:113] op_sel:[1,0]
	v_mov_b32_e32 v115, v113
	v_fmac_f32_e32 v72, 0xb9800000, v136
	v_fmamk_f32 v71, v136, 0xb9800000, v71
	v_fmac_f32_e32 v70, 0xb9800000, v136
	v_pk_add_f32 v[112:113], v[116:117], v[114:115]
	v_pk_mul_f32 v[114:115], v[70:71], v[70:71]
	v_pk_mul_f32 v[116:117], v[72:73], v[72:73]
	v_fmac_f32_e32 v58, 0xb9800000, v136
	v_pk_mov_b32 v[118:119], v[116:117], v[114:115] op_sel:[1,0]
	v_mov_b32_e32 v117, v115
	v_fmamk_f32 v59, v136, 0xb9800000, v59
	v_fmac_f32_e32 v60, 0xb9800000, v136
	v_mul_f32_e32 v102, v58, v58
	v_pk_add_f32 v[114:115], v[118:119], v[116:117]
	v_fmamk_f32 v61, v136, 0xb9800000, v61
	v_pk_fma_f32 v[116:117], v[58:59], v[58:59], v[102:103] op_sel_hi:[1,1,0]
	v_mul_f32_e32 v102, v60, v60
	v_pk_add_f32 v[112:113], v[112:113], v[112:113] op_sel_hi:[0,1]
	v_pk_add_f32 v[114:115], v[114:115], v[114:115] op_sel_hi:[0,1]
	v_pk_fma_f32 v[118:119], v[60:61], v[60:61], v[102:103] op_sel_hi:[1,1,0]
	v_fmamk_f32 v57, v136, 0xb9800000, v57
	v_fmac_f32_e32 v56, 0xb9800000, v136
	v_fmamk_f32 v55, v136, 0xb9800000, v55
	v_fmac_f32_e32 v54, 0xb9800000, v136
	v_mul_f32_e32 v116, v54, v54
	v_mul_f32_e32 v118, v55, v55
	v_mul_f32_e32 v112, v56, v56
	v_mul_f32_e32 v114, v57, v57
	v_pk_add_f32 v[116:117], v[116:117], v[118:119]
	v_pk_add_f32 v[112:113], v[112:113], v[114:115]
	v_fmamk_f32 v51, v136, 0xb9800000, v51
	v_fmac_f32_e32 v50, 0xb9800000, v136
	v_fmamk_f32 v53, v136, 0xb9800000, v53
	v_fmac_f32_e32 v52, 0xb9800000, v136
	v_pk_add_f32 v[112:113], v[116:117], v[112:113]
	v_pk_mul_f32 v[114:115], v[52:53], v[52:53]
	v_pk_mul_f32 v[116:117], v[50:51], v[50:51]
	v_fmac_f32_e32 v42, 0xb9800000, v136
	v_pk_mov_b32 v[118:119], v[116:117], v[114:115] op_sel:[1,0]
	v_mov_b32_e32 v117, v115
	v_fmamk_f32 v43, v136, 0xb9800000, v43
	v_fmac_f32_e32 v44, 0xb9800000, v136
	v_mul_f32_e32 v102, v42, v42
	v_pk_add_f32 v[114:115], v[118:119], v[116:117]
	v_fmamk_f32 v45, v136, 0xb9800000, v45
	v_pk_fma_f32 v[116:117], v[42:43], v[42:43], v[102:103] op_sel_hi:[1,1,0]
	v_mul_f32_e32 v102, v44, v44
	v_pk_add_f32 v[112:113], v[112:113], v[112:113] op_sel_hi:[0,1]
	v_pk_add_f32 v[114:115], v[114:115], v[114:115] op_sel_hi:[0,1]
	v_pk_fma_f32 v[118:119], v[44:45], v[44:45], v[102:103] op_sel_hi:[1,1,0]
	v_fmamk_f32 v81, v136, 0xb9800000, v81
	v_fmac_f32_e32 v80, 0xb9800000, v136
	v_fmamk_f32 v75, v136, 0xb9800000, v75
	v_fmac_f32_e32 v74, 0xb9800000, v136
	v_mul_f32_e32 v116, v74, v74
	v_mul_f32_e32 v118, v75, v75
	v_mul_f32_e32 v114, v80, v80
	v_mul_f32_e32 v112, v81, v81
	v_pk_add_f32 v[116:117], v[116:117], v[118:119]
	v_pk_add_f32 v[112:113], v[114:115], v[112:113]
	v_fmamk_f32 v99, v136, 0xb9800000, v99
	v_fmac_f32_e32 v98, 0xb9800000, v136
	v_fmamk_f32 v101, v136, 0xb9800000, v101
	v_fmac_f32_e32 v100, 0xb9800000, v136
	v_pk_add_f32 v[112:113], v[116:117], v[112:113]
	v_pk_mul_f32 v[114:115], v[100:101], v[100:101]
	v_pk_mul_f32 v[116:117], v[98:99], v[98:99]
	v_fmac_f32_e32 v94, 0xb9800000, v136
	v_pk_mov_b32 v[118:119], v[116:117], v[114:115] op_sel:[1,0]
	v_mov_b32_e32 v117, v115
	v_fmamk_f32 v95, v136, 0xb9800000, v95
	v_fmac_f32_e32 v96, 0xb9800000, v136
	v_mul_f32_e32 v102, v94, v94
	v_pk_add_f32 v[114:115], v[118:119], v[116:117]
	v_fmamk_f32 v97, v136, 0xb9800000, v97
	v_pk_fma_f32 v[116:117], v[94:95], v[94:95], v[102:103] op_sel_hi:[1,1,0]
	v_mul_f32_e32 v102, v96, v96
	v_pk_add_f32 v[112:113], v[112:113], v[112:113] op_sel_hi:[0,1]
	v_pk_add_f32 v[114:115], v[114:115], v[114:115] op_sel_hi:[0,1]
	v_pk_fma_f32 v[118:119], v[96:97], v[96:97], v[102:103] op_sel_hi:[1,1,0]
	v_fmamk_f32 v85, v136, 0xb9800000, v85
	v_fmac_f32_e32 v84, 0xb9800000, v136
	v_fmamk_f32 v83, v136, 0xb9800000, v83
	v_fmac_f32_e32 v82, 0xb9800000, v136
	v_mul_f32_e32 v116, v82, v82
	v_mul_f32_e32 v118, v83, v83
	v_mul_f32_e32 v114, v84, v84
	v_mul_f32_e32 v112, v85, v85
	v_pk_add_f32 v[116:117], v[116:117], v[118:119]
	v_pk_add_f32 v[112:113], v[114:115], v[112:113]
	v_fmamk_f32 v87, v136, 0xb9800000, v87
	v_pk_add_f32 v[112:113], v[116:117], v[112:113]
	v_fmac_f32_e32 v86, 0xb9800000, v136
	v_fmamk_f32 v89, v136, 0xb9800000, v89
	v_fmac_f32_e32 v88, 0xb9800000, v136
	v_pk_add_f32 v[128:129], v[112:113], v[112:113] op_sel_hi:[0,1]
	v_pk_mul_f32 v[112:113], v[88:89], v[88:89]
	v_pk_mul_f32 v[114:115], v[86:87], v[86:87]
	v_fmac_f32_e32 v76, 0xb9800000, v136
	v_pk_mov_b32 v[116:117], v[114:115], v[112:113] op_sel:[1,0]
	v_mov_b32_e32 v115, v113
	v_pk_add_f32 v[112:113], v[116:117], v[114:115]
	v_fmamk_f32 v77, v136, 0xb9800000, v77
	v_pk_add_f32 v[130:131], v[112:113], v[112:113] op_sel_hi:[0,1]
	global_load_dwordx4 v[112:115], v[14:15], off offset:16
	global_load_dwordx4 v[116:119], v[14:15], off
	global_load_dwordx4 v[120:123], v[16:17], off offset:16
	global_load_dwordx4 v[124:127], v[16:17], off
	v_fmac_f32_e32 v78, 0xb9800000, v136
	v_mul_f32_e32 v102, v76, v76
	v_fmamk_f32 v79, v136, 0xb9800000, v79
	v_pk_fma_f32 v[132:133], v[76:77], v[76:77], v[102:103] op_sel_hi:[1,1,0]
	v_mul_f32_e32 v102, v78, v78
	v_pk_fma_f32 v[134:135], v[78:79], v[78:79], v[102:103] op_sel_hi:[1,1,0]
	v_fmamk_f32 v69, v136, 0xb9800000, v69
	v_fmac_f32_e32 v68, 0xb9800000, v136
	v_fmamk_f32 v67, v136, 0xb9800000, v67
	v_fmac_f32_e32 v66, 0xb9800000, v136
	v_mul_f32_e32 v132, v66, v66
	v_mul_f32_e32 v134, v67, v67
; __device__ __forceinline__ void p6_final_ln(const Frame& F) {
;     ...
;         for (int j = 0; j < 16; ++j) { const f32x4 d = z[j] - mean; z[j] = d; q += (d[0] * d[0] + d[1] * d[1]) + (d[2] * d[2] + d[3] * d[3]); }
;         const float rstd = __builtin_amdgcn_rsqf(wave_sum(q) * (1.f / DM) + LN_EPS);
;         float* yr = F.out + (size_t)m * DM;
; #pragma unroll
;         for (int j = 0; j < 8; ++j) { const int col = j * 512 + lane * 8;
;             const f32x4 ga = *(const f32x4*)(F.ln_g + col), gb = *(const f32x4*)(F.ln_g + col + 4), ba = *(const f32x4*)(F.ln_b + col), bb = *(const f32x4*)(F.ln_b + col + 4);
;             *(f32x4*)(yr + col) = z[2 * j] * rstd * ga + ba; *(f32x4*)(yr + col + 4) = z[2 * j + 1] * rstd * gb + bb; }
	v_mul_f32_e32 v130, v68, v68
	v_mul_f32_e32 v128, v69, v69
	v_pk_add_f32 v[132:133], v[132:133], v[134:135]
	v_pk_add_f32 v[128:129], v[130:131], v[128:129]
	v_fmamk_f32 v63, v136, 0xb9800000, v63
	v_fmac_f32_e32 v62, 0xb9800000, v136
	v_fmamk_f32 v65, v136, 0xb9800000, v65
	v_fmac_f32_e32 v64, 0xb9800000, v136
	v_pk_add_f32 v[128:129], v[132:133], v[128:129]
	v_pk_mul_f32 v[130:131], v[64:65], v[64:65]
	v_pk_mul_f32 v[132:133], v[62:63], v[62:63]
	v_fmac_f32_e32 v2, 0xb9800000, v136
	v_pk_mov_b32 v[134:135], v[132:133], v[130:131] op_sel:[1,0]
	v_mov_b32_e32 v133, v131
	v_fmamk_f32 v3, v136, 0xb9800000, v3
	v_fmac_f32_e32 v0, 0xb9800000, v136
	v_mul_f32_e32 v102, v2, v2
	v_pk_add_f32 v[130:131], v[134:135], v[132:133]
	v_fmamk_f32 v1, v136, 0xb9800000, v1
	v_pk_fma_f32 v[132:133], v[2:3], v[2:3], v[102:103] op_sel_hi:[1,1,0]
	v_mul_f32_e32 v102, v0, v0
	v_pk_add_f32 v[128:129], v[128:129], v[128:129] op_sel_hi:[0,1]
	v_pk_add_f32 v[130:131], v[130:131], v[130:131] op_sel_hi:[0,1]
	v_pk_fma_f32 v[134:135], v[0:1], v[0:1], v[102:103] op_sel_hi:[1,1,0]
	v_fmamk_f32 v47, v136, 0xb9800000, v47
	v_fmac_f32_e32 v46, 0xb9800000, v136
	v_fmamk_f32 v49, v136, 0xb9800000, v49
	v_fmac_f32_e32 v48, 0xb9800000, v136
	v_mul_f32_e32 v132, v48, v48
	v_mul_f32_e32 v134, v49, v49
	v_mul_f32_e32 v130, v46, v46
	v_mul_f32_e32 v128, v47, v47
	v_pk_add_f32 v[132:133], v[132:133], v[134:135]
	v_pk_add_f32 v[128:129], v[130:131], v[128:129]
	s_nop 0
	v_pk_add_f32 v[128:129], v[132:133], v[128:129]
	s_nop 0
	v_add_f32_e32 v102, v128, v129
	ds_bpermute_b32 v128, v5, v102
	s_waitcnt lgkmcnt(0)
	v_add_f32_e32 v102, v102, v128
	ds_bpermute_b32 v128, v7, v102
	s_waitcnt lgkmcnt(0)
	v_add_f32_e32 v102, v102, v128
	ds_bpermute_b32 v128, v9, v102
	s_waitcnt lgkmcnt(0)
	v_add_f32_e32 v102, v102, v128
	ds_bpermute_b32 v128, v11, v102
	s_waitcnt lgkmcnt(0)
	v_add_f32_e32 v102, v102, v128
	ds_bpermute_b32 v128, v13, v102
	s_waitcnt lgkmcnt(0)
	v_add_f32_e32 v102, v102, v128
	ds_bpermute_b32 v128, v103, v102
	s_waitcnt lgkmcnt(0)
	v_add_f32_e32 v102, v102, v128
	v_fmamk_f32 v102, v102, 0x39800000, v106
	v_rsq_f32_e32 v102, v102
	s_nop 0
	v_pk_mul_f32 v[128:129], v[92:93], v[102:103] op_sel_hi:[1,0]
	v_pk_mul_f32 v[90:91], v[90:91], v[102:103] op_sel_hi:[1,0]
	v_pk_mul_f32 v[70:71], v[70:71], v[102:103] op_sel_hi:[1,0]
	s_waitcnt vmcnt(0)
	v_pk_fma_f32 v[92:93], v[118:119], v[90:91], v[126:127]
	v_pk_fma_f32 v[90:91], v[116:117], v[128:129], v[124:125]
	global_store_dwordx4 v109, v[90:93], s[12:13]
	v_pk_mul_f32 v[60:61], v[60:61], v[102:103] op_sel_hi:[1,0]
	v_pk_mul_f32 v[58:59], v[58:59], v[102:103] op_sel_hi:[1,0]
	v_pk_mul_f32 v[90:91], v[72:73], v[102:103] op_sel_hi:[1,0]
	v_pk_fma_f32 v[72:73], v[114:115], v[70:71], v[122:123]
	v_pk_fma_f32 v[70:71], v[112:113], v[90:91], v[120:121]
	global_store_dwordx4 v109, v[70:73], s[12:13] offset:16
	global_load_dwordx4 v[70:73], v[16:17], off offset:2048
	s_nop 0
	global_load_dwordx4 v[90:93], v[14:15], off offset:2048
	global_load_dwordx4 v[112:115], v[14:15], off offset:2064
	global_load_dwordx4 v[116:119], v[16:17], off offset:2064
	v_pk_mul_f32 v[56:57], v[56:57], v[102:103] op_sel_hi:[1,0]
	v_pk_mul_f32 v[54:55], v[54:55], v[102:103] op_sel_hi:[1,0]
	v_pk_mul_f32 v[52:53], v[52:53], v[102:103] op_sel_hi:[1,0]
	v_pk_mul_f32 v[50:51], v[50:51], v[102:103] op_sel_hi:[1,0]
	v_pk_mul_f32 v[44:45], v[44:45], v[102:103] op_sel_hi:[1,0]
	v_pk_mul_f32 v[42:43], v[42:43], v[102:103] op_sel_hi:[1,0]
	v_pk_mul_f32 v[76:77], v[76:77], v[102:103] op_sel_hi:[1,0]
	v_pk_mul_f32 v[68:69], v[68:69], v[102:103] op_sel_hi:[1,0]
	v_pk_mul_f32 v[66:67], v[66:67], v[102:103] op_sel_hi:[1,0]
	v_pk_mul_f32 v[64:65], v[64:65], v[102:103] op_sel_hi:[1,0]
	v_pk_mul_f32 v[62:63], v[62:63], v[102:103] op_sel_hi:[1,0]
	v_pk_mul_f32 v[46:47], v[46:47], v[102:103] op_sel_hi:[1,0]
	v_pk_mul_f32 v[48:49], v[48:49], v[102:103] op_sel_hi:[1,0]
	s_waitcnt vmcnt(2)
	v_pk_fma_f32 v[58:59], v[90:91], v[58:59], v[70:71]
	v_pk_fma_f32 v[60:61], v[92:93], v[60:61], v[72:73]
	s_waitcnt vmcnt(0)
; __device__ __forceinline__ void p6_final_ln(const Frame& F) {
;     ...
;         float* yr = F.out + (size_t)m * DM;
; #pragma unroll
;         for (int j = 0; j < 8; ++j) { const int col = j * 512 + lane * 8;
;             const f32x4 ga = *(const f32x4*)(F.ln_g + col), gb = *(const f32x4*)(F.ln_g + col + 4), ba = *(const f32x4*)(F.ln_b + col), bb = *(const f32x4*)(F.ln_b + col + 4);
;             *(f32x4*)(yr + col) = z[2 * j] * rstd * ga + ba; *(f32x4*)(yr + col + 4) = z[2 * j + 1] * rstd * gb + bb; }
	v_pk_fma_f32 v[54:55], v[112:113], v[54:55], v[116:117]
	v_pk_fma_f32 v[56:57], v[114:115], v[56:57], v[118:119]
	global_store_dwordx4 v109, v[58:61], s[12:13] offset:2048
	global_store_dwordx4 v109, v[54:57], s[12:13] offset:2064
	global_load_dwordx4 v[54:57], v[20:21], off
	s_nop 0
	global_load_dwordx4 v[58:61], v[18:19], off
	global_load_dwordx4 v[70:73], v[18:19], off offset:16
	global_load_dwordx4 v[90:93], v[20:21], off offset:16
	s_waitcnt vmcnt(2)
	v_pk_fma_f32 v[50:51], v[58:59], v[50:51], v[54:55]
	v_pk_fma_f32 v[52:53], v[60:61], v[52:53], v[56:57]
	s_waitcnt vmcnt(0)
	v_pk_fma_f32 v[42:43], v[70:71], v[42:43], v[90:91]
	v_pk_fma_f32 v[44:45], v[72:73], v[44:45], v[92:93]
	global_store_dwordx4 v104, v[50:53], s[12:13]
	global_store_dwordx4 v104, v[42:45], s[12:13] offset:16
	global_load_dwordx4 v[42:45], v[24:25], off
	s_nop 0
	global_load_dwordx4 v[50:53], v[22:23], off
	global_load_dwordx4 v[54:57], v[22:23], off offset:16
	global_load_dwordx4 v[58:61], v[24:25], off offset:16
	v_pk_mul_f32 v[70:71], v[80:81], v[102:103] op_sel_hi:[1,0]
	v_pk_mul_f32 v[72:73], v[74:75], v[102:103] op_sel_hi:[1,0]
	v_pk_mul_f32 v[74:75], v[84:85], v[102:103] op_sel_hi:[1,0]
	v_pk_mul_f32 v[80:81], v[82:83], v[102:103] op_sel_hi:[1,0]
	s_waitcnt vmcnt(2)
	v_pk_fma_f32 v[42:43], v[50:51], v[72:73], v[42:43]
	v_pk_fma_f32 v[44:45], v[52:53], v[70:71], v[44:45]
	global_store_dwordx4 v105, v[42:45], s[12:13]
	v_pk_mul_f32 v[70:71], v[96:97], v[102:103] op_sel_hi:[1,0]
	v_pk_mul_f32 v[72:73], v[94:95], v[102:103] op_sel_hi:[1,0]
	v_pk_mul_f32 v[44:45], v[100:101], v[102:103] op_sel_hi:[1,0]
	v_pk_mul_f32 v[42:43], v[98:99], v[102:103] op_sel_hi:[1,0]
	s_waitcnt vmcnt(1)
	v_pk_fma_f32 v[44:45], v[56:57], v[44:45], v[60:61]
	v_pk_fma_f32 v[42:43], v[54:55], v[42:43], v[58:59]
	global_store_dwordx4 v105, v[42:45], s[12:13] offset:16
	global_load_dwordx4 v[42:45], v[28:29], off
	s_nop 0
	global_load_dwordx4 v[50:53], v[26:27], off
	global_load_dwordx4 v[54:57], v[26:27], off offset:16
	global_load_dwordx4 v[58:61], v[28:29], off offset:16
	s_waitcnt vmcnt(2)
	v_pk_fma_f32 v[42:43], v[50:51], v[72:73], v[42:43]
	v_pk_fma_f32 v[44:45], v[52:53], v[70:71], v[44:45]
	s_waitcnt vmcnt(0)
	v_pk_fma_f32 v[50:51], v[54:55], v[80:81], v[58:59]
	v_pk_fma_f32 v[52:53], v[56:57], v[74:75], v[60:61]
	global_store_dwordx4 v107, v[42:45], s[12:13]
	global_store_dwordx4 v107, v[50:53], s[12:13] offset:16
	global_load_dwordx4 v[42:45], v[32:33], off
	s_nop 0
	global_load_dwordx4 v[50:53], v[30:31], off
	global_load_dwordx4 v[54:57], v[30:31], off offset:16
	global_load_dwordx4 v[58:61], v[32:33], off offset:16
	v_pk_mul_f32 v[70:71], v[88:89], v[102:103] op_sel_hi:[1,0]
	v_pk_mul_f32 v[72:73], v[86:87], v[102:103] op_sel_hi:[1,0]
	v_pk_mul_f32 v[74:75], v[78:79], v[102:103] op_sel_hi:[1,0]
	s_waitcnt vmcnt(2)
	v_pk_fma_f32 v[42:43], v[50:51], v[72:73], v[42:43]
	v_pk_fma_f32 v[44:45], v[52:53], v[70:71], v[44:45]
	s_waitcnt vmcnt(0)
	v_pk_fma_f32 v[50:51], v[54:55], v[76:77], v[58:59]
	v_pk_fma_f32 v[52:53], v[56:57], v[74:75], v[60:61]
	global_store_dwordx4 v108, v[42:45], s[12:13]
	global_store_dwordx4 v108, v[50:53], s[12:13] offset:16
	global_load_dwordx4 v[42:45], v[36:37], off
	s_nop 0
	global_load_dwordx4 v[50:53], v[34:35], off
	global_load_dwordx4 v[54:57], v[34:35], off offset:16
	global_load_dwordx4 v[58:61], v[36:37], off offset:16
	s_waitcnt vmcnt(2)
	v_pk_fma_f32 v[42:43], v[50:51], v[66:67], v[42:43]
	v_pk_fma_f32 v[44:45], v[52:53], v[68:69], v[44:45]
	s_waitcnt vmcnt(0)
	v_pk_fma_f32 v[50:51], v[54:55], v[62:63], v[58:59]
	v_pk_fma_f32 v[52:53], v[56:57], v[64:65], v[60:61]
	global_store_dwordx4 v111, v[42:45], s[12:13]
	global_store_dwordx4 v111, v[50:53], s[12:13] offset:16
	global_load_dwordx4 v[42:45], v[40:41], off
	s_nop 0
	global_load_dwordx4 v[50:53], v[38:39], off
	global_load_dwordx4 v[54:57], v[38:39], off offset:16
	global_load_dwordx4 v[58:61], v[40:41], off offset:16
	v_pk_mul_f32 v[62:63], v[0:1], v[102:103] op_sel_hi:[1,0]
	v_pk_mul_f32 v[0:1], v[2:3], v[102:103] op_sel_hi:[1,0]
	s_waitcnt vmcnt(2)
	v_pk_fma_f32 v[2:3], v[52:53], v[62:63], v[44:45]
	v_pk_fma_f32 v[0:1], v[50:51], v[0:1], v[42:43]
	s_waitcnt vmcnt(0)
	v_pk_fma_f32 v[42:43], v[48:49], v[54:55], v[58:59]
	v_pk_fma_f32 v[44:45], v[46:47], v[56:57], v[60:61]
	global_store_dwordx4 v110, v[0:3], s[12:13]
	global_store_dwordx4 v110, v[42:45], s[12:13] offset:16
	s_cbranch_scc0 .LBB0_578
